# stagger: waves 4-7 start each head's attention key steps half a step late (s_sleep 5 after the head barrier)
# baseline (speedup 1.0000x reference)
; __device__ __forceinline__ unsigned pk2(float lo, float hi) { unsigned r; asm volatile("v_cvt_pk_bf16_f32 %0, %1, %2" : "=v"(r) : "v"(lo), "v"(hi)); return r; }
; __device__ __forceinline__ void qk_prep_store(u32x4 a, u32x4 b, const float* gain, int sub, int pos, float scale, bf16_t* dst, int lane) {
;     ...
;     u32x4 o0, o1;
;     o0.x = pk2(x[0] * scale, x[1] * scale); o0.y = pk2(x[2] * scale, x[3] * scale); o0.z = pk2(x[4] * scale, x[5] * scale); o0.w = pk2(x[6] * scale, x[7] * scale);
;     o1.x = pk2(x[8] * scale, x[9] * scale); o1.y = pk2(x[10] * scale, x[11] * scale); o1.z = pk2(x[12] * scale, x[13] * scale); o1.w = pk2(x[14] * scale, x[15] * scale);
;     *(u32x4*)dst = o0; *(u32x4*)(dst + 8) = o1;
; __device__ __forceinline__ void ph_attn(KP p, int l, unsigned char* sm, int wv) {
;     ...
;                 qk_prep_store(qsa, qsb, qg, sub, Q0rel + row, 0.125f * 1.4426950408889634f, Qs + row * 72 + sub * 16, lane);
;             }
;             __syncthreads();
.LBB0_846:
	s_or_b64 exec, exec, s[2:3]
	v_mul_f32_e32 v41, 0x3e38aa3b, v50
	v_mul_f32_e32 v43, 0x3e38aa3b, v51
	v_cvt_pk_bf16_f32 v50, v41, v43
	v_mul_f32_e32 v41, 0x3e38aa3b, v48
	v_mul_f32_e32 v43, 0x3e38aa3b, v49
	v_cvt_pk_bf16_f32 v51, v41, v43
	v_mul_f32_e32 v41, 0x3e38aa3b, v46
	v_mul_f32_e32 v34, 0x3e38aa3b, v34
	v_mul_f32_e32 v35, 0x3e38aa3b, v35
	v_readlane_b32 s2, v254, 22
	v_mul_f32_e32 v43, 0x3e38aa3b, v47
	v_cvt_pk_bf16_f32 v52, v41, v43
	v_mul_f32_e32 v41, 0x3e38aa3b, v42
	v_mul_f32_e32 v42, 0x3e38aa3b, v45
	v_cvt_pk_bf16_f32 v53, v41, v42
	v_mul_f32_e32 v38, 0x3e38aa3b, v38
	v_mul_f32_e32 v39, 0x3e38aa3b, v39
	v_cvt_pk_bf16_f32 v46, v38, v39
	v_mul_f32_e32 v36, 0x3e38aa3b, v36
	v_mul_f32_e32 v37, 0x3e38aa3b, v37
	v_cvt_pk_bf16_f32 v47, v36, v37
	v_cvt_pk_bf16_f32 v48, v34, v35
	v_mul_f32_e32 v34, 0x3e38aa3b, v40
	v_mul_f32_e32 v35, 0x3e38aa3b, v44
	v_readlane_b32 s3, v254, 23
	v_cvt_pk_bf16_f32 v49, v34, v35
	ds_write_b128 v98, v[50:53]
	ds_write_b128 v98, v[46:49] offset:16
	s_waitcnt lgkmcnt(0)
	s_barrier
	v_readlane_b32 s98, v254, 4
	s_nop 0
	s_cmpk_lt_u32 s98, 0x100
	s_cbranch_scc1 .Lmy_attn_stagger_done
	s_sleep 5
